# STAGGER-ODD: odd workgroups start GEMM1b and GEMM3 one s_sleep 80 later so the two halves' epilogue store bursts do not coincide (on STAGGER-P2)
# baseline (speedup 1.0000x reference)
.LBB0_665:
	s_or_b64 exec, exec, s[6:7]
	s_bitcmp1_b32 s75, 0
	s_cbranch_scc0 .Lstagodd_1
	s_sleep 80
.Lstagodd_1:
	s_cmpk_lt_i32 s75, 0x500
	s_cselect_b64 s[4:5], -1, 0
	s_cmpk_gt_i32 s75, 0x4ff
	v_readfirstlane_b32 s3, v0
	s_waitcnt lgkmcnt(0)
	s_barrier
	s_cbranch_scc1 .LBB0_667
	s_ashr_i32 s0, s75, 31
	s_lshr_b32 s0, s0, 29
	s_add_i32 s0, s75, s0
	s_ashr_i32 s1, s0, 3
	s_and_b32 s0, s0, -8
	s_sub_i32 s0, s75, s0
	s_cmp_lt_i32 s0, 0
	s_movk_i32 s2, 0xa1
	s_cselect_b32 s2, s2, 0xa0
	s_mul_i32 s0, s0, s2
	s_add_i32 s0, s0, s1
	s_ashr_i32 s1, s0, 31
	s_lshr_b32 s1, s1, 25
	s_add_i32 s1, s0, s1
	s_ashr_i32 s2, s1, 7
	s_and_b32 s1, s1, 0xffffff80
	s_sub_i32 s0, s0, s1
	s_bfe_i32 s1, s0, 0x80000
	s_bfe_u32 s1, s1, 0x3000c
	s_add_i32 s1, s0, s1
	s_bfe_i32 s6, s1, 0x80000
	s_and_b32 s1, s1, 0xf8
	s_sub_i32 s0, s0, s1
	s_lshl_b32 s2, s2, 3
	s_sext_i32_i16 s7, s6
	s_sext_i32_i8 s0, s0
	s_add_i32 s6, s2, s0
	s_ashr_i32 s10, s7, 3

.LBB0_1240:
	s_cmp_lt_i32 s62, 11
	s_cselect_b64 s[0:1], -1, 0
	s_and_b64 s[12:13], s[0:1], s[6:7]
	s_andn2_b64 vcc, exec, s[12:13]
	s_cbranch_vccnz .LBB0_1287
	s_bitcmp1_b32 s75, 0
	s_cbranch_scc0 .Lstagodd_2
	s_sleep 80
.Lstagodd_2:
	s_cmpk_lt_i32 s75, 0xa00
	s_cselect_b64 s[4:5], -1, 0
	s_cmpk_gt_i32 s75, 0x9ff
	v_readfirstlane_b32 s8, v0
	s_cbranch_scc1 .LBB0_1243
	s_ashr_i32 s0, s75, 31
	s_lshr_b32 s0, s0, 29
	s_add_i32 s0, s75, s0
	s_ashr_i32 s1, s0, 3
	s_and_b32 s0, s0, -8
	s_sub_i32 s0, s75, s0
	s_cmp_lt_i32 s0, 0
	s_movk_i32 s2, 0x141
	s_cselect_b32 s2, s2, 0x140
	s_mul_i32 s0, s0, s2
	s_add_i32 s0, s0, s1
	s_ashr_i32 s1, s0, 31
	s_lshr_b32 s1, s1, 24
	s_add_i32 s1, s0, s1
	s_ashr_i32 s2, s1, 8
	s_and_b32 s1, s1, 0xffffff00
	s_sub_i32 s0, s0, s1
	s_sext_i32_i16 s1, s0
	s_bfe_u32 s1, s1, 0x3001c
	s_add_i32 s1, s0, s1
	s_sext_i32_i16 s3, s1
	s_and_b32 s1, s1, 0xfff8
	s_sub_i32 s0, s0, s1
	s_lshl_b32 s2, s2, 3
	s_sext_i32_i16 s0, s0
	s_waitcnt lgkmcnt(0)
	s_add_i32 s20, s2, s0
	s_ashr_i32 s6, s3, 3
